# grid seams: acquire invalidate issued at arrival (overlapped with the arrival atomic / write-back) instead of after the release; no cached loads are issued between arrival and release
# speedup vs baseline: 1.0326x; 1.0113x over previous
.LBB0_88:
	v_readlane_b32 s9, v246, 5
	s_lshl_b32 s9, s9, 8
	v_readlane_b32 s10, v246, 3
	v_readlane_b32 s11, v246, 4
	s_add_u32 s10, s10, s9
	s_addc_u32 s11, s11, 0
	v_mov_b32_e32 v1, 0x1000
	v_mov_b32_e32 v3, 1
	v_sub_u32_e32 v4, 0, v2
	global_atomic_add v3, v1, v3, s[10:11] offset:1024 sc0
	v_cvt_f32_u32_e32 v1, v2
	v_rcp_iflag_f32_e32 v1, v1
	s_nop 0
	v_mul_f32_e32 v1, 0x4f7ffffe, v1
	v_cvt_u32_f32_e32 v1, v1
	v_mul_lo_u32 v4, v4, v1
	v_mul_hi_u32 v4, v1, v4
	v_add_u32_e32 v1, v1, v4
	s_waitcnt vmcnt(0)
	v_mul_hi_u32 v1, v3, v1
	v_mul_lo_u32 v4, v1, v2
	v_sub_u32_e32 v4, v3, v4
	v_add_u32_e32 v5, 1, v1
	v_cmp_ge_u32_e32 vcc, v4, v2
	v_add_u32_e32 v3, 1, v3
	s_nop 0
	v_cndmask_b32_e32 v1, v1, v5, vcc
	v_sub_u32_e32 v5, v4, v2
	v_cndmask_b32_e32 v4, v4, v5, vcc
	v_add_u32_e32 v5, 1, v1
	v_cmp_ge_u32_e32 vcc, v4, v2
	s_nop 1
	v_cndmask_b32_e32 v1, v1, v5, vcc
	v_mul_lo_u32 v4, v2, v1
	v_add_u32_e32 v2, v4, v2
	v_cmp_ne_u32_e32 vcc, v3, v2
	s_and_saveexec_b64 s[12:13], vcc
	s_xor_b64 s[12:13], exec, s[12:13]
	s_cbranch_execz .LBB0_102
	s_waitcnt lgkmcnt(0)
	v_mov_b32_e32 v0, 0x2000
	global_load_dword v0, v0, s[10:11] offset:1024 sc1
	buffer_inv sc1
	s_add_u32 s18, s10, 0x2400
	s_addc_u32 s19, s11, 0
	s_waitcnt vmcnt(0)
	v_cmp_eq_u32_e32 vcc, v0, v1
	s_and_saveexec_b64 s[14:15], vcc
	s_cbranch_execz .LBB0_101
	s_add_u32 s16, s54, 0xd600200
	s_addc_u32 s17, s55, 0
	s_mov_b32 s9, 1
	s_mov_b64 s[20:21], 0
	v_mov_b32_e32 v0, 0
	s_branch .LBB0_92

.LBB0_101:
	s_or_b64 exec, exec, s[14:15]
	s_waitcnt vmcnt(0)
	s_nop 0
	s_waitcnt vmcnt(0)
.LBB0_102:
	s_andn2_saveexec_b64 s[12:13], s[12:13]
	s_cbranch_execz .LBB0_120
	s_mov_b64 s[12:13], exec
	buffer_wbl2 sc1
	buffer_inv sc1
	s_waitcnt lgkmcnt(0)
	s_waitcnt vmcnt(0)
	v_mbcnt_lo_u32_b32 v1, s12, 0
	v_mbcnt_hi_u32_b32 v1, s13, v1
	v_cmp_eq_u32_e32 vcc, 0, v1
	s_and_saveexec_b64 s[14:15], vcc
	s_cbranch_execz .LBB0_105
	s_bcnt1_i32_b64 s9, s[12:13]
	v_mov_b32_e32 v2, 0xd603000
	v_mov_b32_e32 v3, s9
	global_atomic_add v2, v2, v3, s[54:55] offset:1024 sc0

.LBB0_119:
	s_or_b64 exec, exec, s[12:13]
	v_mov_b32_e32 v0, 0x2000
	v_mov_b32_e32 v1, 1
	s_waitcnt vmcnt(0)
	s_nop 0
	s_waitcnt vmcnt(0)

.LBB0_150:
	v_readlane_b32 s3, v246, 5
	s_lshl_b32 s3, s3, 8
	v_readlane_b32 s8, v246, 3
	v_readlane_b32 s9, v246, 4
	s_add_u32 s8, s8, s3
	s_addc_u32 s9, s9, 0
	v_mov_b32_e32 v1, 0x1000
	v_mov_b32_e32 v3, 1
	v_sub_u32_e32 v4, 0, v2
	global_atomic_add v3, v1, v3, s[8:9] offset:1024 sc0
	v_cvt_f32_u32_e32 v1, v2
	v_rcp_iflag_f32_e32 v1, v1
	s_nop 0
	v_mul_f32_e32 v1, 0x4f7ffffe, v1
	v_cvt_u32_f32_e32 v1, v1
	v_mul_lo_u32 v4, v4, v1
	v_mul_hi_u32 v4, v1, v4
	v_add_u32_e32 v1, v1, v4
	s_waitcnt vmcnt(0)
	v_mul_hi_u32 v1, v3, v1
	v_mul_lo_u32 v4, v1, v2
	v_sub_u32_e32 v4, v3, v4
	v_add_u32_e32 v5, 1, v1
	v_cmp_ge_u32_e32 vcc, v4, v2
	v_add_u32_e32 v3, 1, v3
	s_nop 0
	v_cndmask_b32_e32 v1, v1, v5, vcc
	v_sub_u32_e32 v5, v4, v2
	v_cndmask_b32_e32 v4, v4, v5, vcc
	v_add_u32_e32 v5, 1, v1
	v_cmp_ge_u32_e32 vcc, v4, v2
	s_nop 1
	v_cndmask_b32_e32 v1, v1, v5, vcc
	v_mul_lo_u32 v4, v2, v1
	v_add_u32_e32 v2, v4, v2
	v_cmp_ne_u32_e32 vcc, v3, v2
	s_and_saveexec_b64 s[10:11], vcc
	s_xor_b64 s[10:11], exec, s[10:11]
	s_cbranch_execz .LBB0_164
	s_waitcnt lgkmcnt(0)
	v_mov_b32_e32 v0, 0x2000
	global_load_dword v0, v0, s[8:9] offset:1024 sc1
	buffer_inv sc1
	s_add_u32 s16, s8, 0x2400
	s_addc_u32 s17, s9, 0
	s_waitcnt vmcnt(0)
	v_cmp_eq_u32_e32 vcc, v0, v1
	s_and_saveexec_b64 s[12:13], vcc
	s_cbranch_execz .LBB0_163
	s_add_u32 s14, s54, 0xd600200
	s_addc_u32 s15, s55, 0
	s_mov_b32 s3, 1
	s_mov_b64 s[18:19], 0
	v_mov_b32_e32 v0, 0
	s_branch .LBB0_154

.LBB0_163:
	s_or_b64 exec, exec, s[12:13]
	s_waitcnt vmcnt(0)
	s_nop 0
	s_waitcnt vmcnt(0)
.LBB0_164:
	s_andn2_saveexec_b64 s[10:11], s[10:11]
	s_cbranch_execz .LBB0_182
	s_mov_b64 s[10:11], exec
	buffer_wbl2 sc1
	buffer_inv sc1
	s_waitcnt lgkmcnt(0)
	s_waitcnt vmcnt(0)
	v_mbcnt_lo_u32_b32 v1, s10, 0
	v_mbcnt_hi_u32_b32 v1, s11, v1
	v_cmp_eq_u32_e32 vcc, 0, v1
	s_and_saveexec_b64 s[12:13], vcc
	s_cbranch_execz .LBB0_167
	s_bcnt1_i32_b64 s3, s[10:11]
	v_mov_b32_e32 v2, 0xd603000
	v_mov_b32_e32 v3, s3
	global_atomic_add v2, v2, v3, s[54:55] offset:1024 sc0

.LBB0_181:
	s_or_b64 exec, exec, s[10:11]
	v_mov_b32_e32 v0, 0x2000
	v_mov_b32_e32 v1, 1
	s_waitcnt vmcnt(0)
	s_nop 0
	s_waitcnt vmcnt(0)

.LBB0_223:
	v_readlane_b32 s3, v246, 5
	s_lshl_b32 s3, s3, 8
	v_readlane_b32 s6, v246, 3
	v_readlane_b32 s7, v246, 4
	s_add_u32 s6, s6, s3
	s_addc_u32 s7, s7, 0
	v_mov_b32_e32 v1, 0x1000
	v_mov_b32_e32 v3, 1
	v_sub_u32_e32 v4, 0, v2
	global_atomic_add v3, v1, v3, s[6:7] offset:1024 sc0
	v_cvt_f32_u32_e32 v1, v2
	v_rcp_iflag_f32_e32 v1, v1
	s_nop 0
	v_mul_f32_e32 v1, 0x4f7ffffe, v1
	v_cvt_u32_f32_e32 v1, v1
	v_mul_lo_u32 v4, v4, v1
	v_mul_hi_u32 v4, v1, v4
	v_add_u32_e32 v1, v1, v4
	s_waitcnt vmcnt(0)
	v_mul_hi_u32 v1, v3, v1
	v_mul_lo_u32 v4, v1, v2
	v_sub_u32_e32 v4, v3, v4
	v_add_u32_e32 v5, 1, v1
	v_cmp_ge_u32_e32 vcc, v4, v2
	v_add_u32_e32 v3, 1, v3
	s_nop 0
	v_cndmask_b32_e32 v1, v1, v5, vcc
	v_sub_u32_e32 v5, v4, v2
	v_cndmask_b32_e32 v4, v4, v5, vcc
	v_add_u32_e32 v5, 1, v1
	v_cmp_ge_u32_e32 vcc, v4, v2
	s_nop 1
	v_cndmask_b32_e32 v1, v1, v5, vcc
	v_mul_lo_u32 v4, v2, v1
	v_add_u32_e32 v2, v4, v2
	v_cmp_ne_u32_e32 vcc, v3, v2
	s_and_saveexec_b64 s[8:9], vcc
	s_xor_b64 s[8:9], exec, s[8:9]
	s_cbranch_execz .LBB0_237
	s_waitcnt lgkmcnt(0)
	v_mov_b32_e32 v0, 0x2000
	global_load_dword v0, v0, s[6:7] offset:1024 sc1
	buffer_inv sc1
	s_add_u32 s14, s6, 0x2400
	s_addc_u32 s15, s7, 0
	s_waitcnt vmcnt(0)
	v_cmp_eq_u32_e32 vcc, v0, v1
	s_and_saveexec_b64 s[10:11], vcc
	s_cbranch_execz .LBB0_236
	s_add_u32 s12, s54, 0xd600200
	s_addc_u32 s13, s55, 0
	s_mov_b32 s3, 1
	s_mov_b64 s[16:17], 0
	v_mov_b32_e32 v0, 0
	s_branch .LBB0_227

.LBB0_236:
	s_or_b64 exec, exec, s[10:11]
	s_waitcnt vmcnt(0)
	s_nop 0
	s_waitcnt vmcnt(0)
.LBB0_237:
	s_andn2_saveexec_b64 s[8:9], s[8:9]
	s_cbranch_execz .LBB0_255
	s_mov_b64 s[8:9], exec
	buffer_wbl2 sc1
	buffer_inv sc1
	s_waitcnt lgkmcnt(0)
	s_waitcnt vmcnt(0)
	v_mbcnt_lo_u32_b32 v1, s8, 0
	v_mbcnt_hi_u32_b32 v1, s9, v1
	v_cmp_eq_u32_e32 vcc, 0, v1
	s_and_saveexec_b64 s[10:11], vcc
	s_cbranch_execz .LBB0_240
	s_bcnt1_i32_b64 s3, s[8:9]
	v_mov_b32_e32 v2, 0xd603000
	v_mov_b32_e32 v3, s3
	global_atomic_add v2, v2, v3, s[54:55] offset:1024 sc0

.LBB0_254:
	s_or_b64 exec, exec, s[8:9]
	v_mov_b32_e32 v0, 0x2000
	v_mov_b32_e32 v1, 1
	s_waitcnt vmcnt(0)
	s_nop 0
	s_waitcnt vmcnt(0)

.LBB0_589:
	v_readlane_b32 s3, v246, 5
	s_lshl_b32 s3, s3, 8
	v_readlane_b32 s6, v246, 3
	v_readlane_b32 s7, v246, 4
	s_add_u32 s6, s6, s3
	s_addc_u32 s7, s7, 0
	v_mov_b32_e32 v1, 0x1000
	v_mov_b32_e32 v3, 1
	v_sub_u32_e32 v4, 0, v2
	global_atomic_add v3, v1, v3, s[6:7] offset:1024 sc0
	v_cvt_f32_u32_e32 v1, v2
	v_rcp_iflag_f32_e32 v1, v1
	s_nop 0
	v_mul_f32_e32 v1, 0x4f7ffffe, v1
	v_cvt_u32_f32_e32 v1, v1
	v_mul_lo_u32 v4, v4, v1
	v_mul_hi_u32 v4, v1, v4
	v_add_u32_e32 v1, v1, v4
	s_waitcnt vmcnt(0)
	v_mul_hi_u32 v1, v3, v1
	v_mul_lo_u32 v4, v1, v2
	v_sub_u32_e32 v4, v3, v4
	v_add_u32_e32 v5, 1, v1
	v_cmp_ge_u32_e32 vcc, v4, v2
	v_add_u32_e32 v3, 1, v3
	s_nop 0
	v_cndmask_b32_e32 v1, v1, v5, vcc
	v_sub_u32_e32 v5, v4, v2
	v_cndmask_b32_e32 v4, v4, v5, vcc
	v_add_u32_e32 v5, 1, v1
	v_cmp_ge_u32_e32 vcc, v4, v2
	s_nop 1
	v_cndmask_b32_e32 v1, v1, v5, vcc
	v_mul_lo_u32 v4, v2, v1
	v_add_u32_e32 v2, v4, v2
	v_cmp_ne_u32_e32 vcc, v3, v2
	s_and_saveexec_b64 s[8:9], vcc
	s_xor_b64 s[8:9], exec, s[8:9]
	s_cbranch_execz .LBB0_603
	s_waitcnt lgkmcnt(0)
	v_mov_b32_e32 v0, 0x2000
	global_load_dword v0, v0, s[6:7] offset:1024 sc1
	buffer_inv sc1
	s_add_u32 s22, s6, 0x2400
	s_addc_u32 s23, s7, 0
	s_waitcnt vmcnt(0)
	v_cmp_eq_u32_e32 vcc, v0, v1
	s_and_saveexec_b64 s[10:11], vcc
	s_cbranch_execz .LBB0_602
	s_add_u32 s14, s54, 0xd600200
	s_addc_u32 s15, s55, 0
	s_mov_b32 s3, 1
	s_mov_b64 s[28:29], 0
	v_mov_b32_e32 v0, 0
	s_branch .LBB0_593

.LBB0_844:
	v_readlane_b32 s3, v246, 5
	s_lshl_b32 s3, s3, 8
	v_readlane_b32 s6, v246, 3
	v_readlane_b32 s7, v246, 4
	s_add_u32 s6, s6, s3
	s_addc_u32 s7, s7, 0
	v_mov_b32_e32 v1, 0x1000
	v_mov_b32_e32 v3, 1
	v_sub_u32_e32 v4, 0, v2
	global_atomic_add v3, v1, v3, s[6:7] offset:1024 sc0
	v_cvt_f32_u32_e32 v1, v2
	v_rcp_iflag_f32_e32 v1, v1
	s_nop 0
	v_mul_f32_e32 v1, 0x4f7ffffe, v1
	v_cvt_u32_f32_e32 v1, v1
	v_mul_lo_u32 v4, v4, v1
	v_mul_hi_u32 v4, v1, v4
	v_add_u32_e32 v1, v1, v4
	s_waitcnt vmcnt(0)
	v_mul_hi_u32 v1, v3, v1
	v_mul_lo_u32 v4, v1, v2
	v_sub_u32_e32 v4, v3, v4
	v_add_u32_e32 v5, 1, v1
	v_cmp_ge_u32_e32 vcc, v4, v2
	v_add_u32_e32 v3, 1, v3
	s_nop 0
	v_cndmask_b32_e32 v1, v1, v5, vcc
	v_sub_u32_e32 v5, v4, v2
	v_cndmask_b32_e32 v4, v4, v5, vcc
	v_add_u32_e32 v5, 1, v1
	v_cmp_ge_u32_e32 vcc, v4, v2
	s_nop 1
	v_cndmask_b32_e32 v1, v1, v5, vcc
	v_mul_lo_u32 v4, v2, v1
	v_add_u32_e32 v2, v4, v2
	v_cmp_ne_u32_e32 vcc, v3, v2
	s_and_saveexec_b64 s[8:9], vcc
	s_xor_b64 s[8:9], exec, s[8:9]
	s_cbranch_execz .LBB0_858
	s_waitcnt lgkmcnt(0)
	v_mov_b32_e32 v0, 0x2000
	global_load_dword v0, v0, s[6:7] offset:1024 sc1
	buffer_inv sc1
	s_add_u32 s22, s6, 0x2400
	s_addc_u32 s23, s7, 0
	s_waitcnt vmcnt(0)
	v_cmp_eq_u32_e32 vcc, v0, v1
	s_and_saveexec_b64 s[10:11], vcc
	s_cbranch_execz .LBB0_857
	s_add_u32 s20, s54, 0xd600200
	s_addc_u32 s21, s55, 0
	s_mov_b32 s3, 1
	s_mov_b64 s[60:61], 0
	v_mov_b32_e32 v0, 0
	s_branch .LBB0_848
